# NSA: branch-epilogue mix/gate reads prefetched in one burst, false V-load waits at attend-loop heads removed, cmp gate reads hoisted
# speedup vs baseline: 1.1981x; 1.0281x over previous
.LBB0_1234:
	v_readlane_b32 s4, v254, 13
	v_readlane_b32 s8, v254, 17
	v_readlane_b32 s9, v254, 18
	v_readlane_b32 s5, v254, 14
	s_movk_i32 s4, 0x60
	v_mov_b64_e32 v[68:69], s[8:9]
	v_mad_u64_u32 v[68:69], s[4:5], v112, s4, v[68:69]
	s_mul_i32 s4, s24, 48
	s_mov_b32 s5, s75
	v_lshl_add_u64 v[154:155], v[68:69], 0, s[4:5]
	global_load_dword v66, v[154:155], off
	global_load_dword v70, v[154:155], off offset:12
	global_load_dword v72, v[154:155], off offset:24
	global_load_dword v74, v[154:155], off offset:36
	v_mov_b64_e32 v[68:69], s[88:89]
	s_lshl_b32 s74, s0, 1
	s_movk_i32 s0, 0x880
	v_mad_u64_u32 v[68:69], s[4:5], v112, s0, v[68:69]
	v_mov_b32_e32 v151, v0
	v_lshl_add_u64 v[68:69], v[68:69], 0, s[74:75]
	v_lshl_add_u64 v[152:153], v[68:69], 0, v[150:151]
	s_cmp_gt_u32 s1, 63
	v_readlane_b32 s6, v254, 15
	v_readlane_b32 s7, v254, 16
	v_readlane_b32 s10, v254, 19
	v_readlane_b32 s11, v254, 20
	v_readlane_b32 s12, v254, 21
	v_readlane_b32 s13, v254, 22
	v_readlane_b32 s14, v254, 23
	v_readlane_b32 s15, v254, 24
	v_readlane_b32 s16, v254, 25
	v_readlane_b32 s17, v254, 26
	v_readlane_b32 s18, v254, 27
	v_readlane_b32 s19, v254, 28
	s_waitcnt vmcnt(0)
	v_pk_mul_f32 v[26:27], v[26:27], v[66:67] op_sel_hi:[1,0]
	v_pk_mul_f32 v[28:29], v[28:29], v[66:67] op_sel_hi:[1,0]
	v_pk_mul_f32 v[62:63], v[62:63], v[66:67] op_sel_hi:[1,0]
	v_pk_mul_f32 v[64:65], v[64:65], v[66:67] op_sel_hi:[1,0]
	v_pk_mul_f32 v[58:59], v[58:59], v[66:67] op_sel_hi:[1,0]
	v_pk_mul_f32 v[60:61], v[60:61], v[66:67] op_sel_hi:[1,0]
	v_pk_mul_f32 v[54:55], v[54:55], v[66:67] op_sel_hi:[1,0]
	v_pk_mul_f32 v[56:57], v[56:57], v[66:67] op_sel_hi:[1,0]
	v_cvt_pk_bf16_f32 v26, v26, v27
	v_cvt_pk_bf16_f32 v27, v28, v29
	v_cvt_pk_bf16_f32 v28, v62, v63
	v_cvt_pk_bf16_f32 v29, v64, v65
	v_cvt_pk_bf16_f32 v58, v58, v59
	v_cvt_pk_bf16_f32 v59, v60, v61
	v_cvt_pk_bf16_f32 v54, v54, v55
	v_cvt_pk_bf16_f32 v55, v56, v57
	global_store_dwordx2 v[152:153], v[26:27], off
	global_store_dwordx2 v[152:153], v[28:29], off offset:32
	global_store_dwordx2 v[152:153], v[58:59], off offset:64
	global_store_dwordx2 v[152:153], v[54:55], off offset:96
	v_pk_mul_f32 v[28:29], v[50:51], v[70:71] op_sel_hi:[1,0]
	v_pk_mul_f32 v[50:51], v[52:53], v[70:71] op_sel_hi:[1,0]
	v_pk_mul_f32 v[46:47], v[46:47], v[70:71] op_sel_hi:[1,0]
	v_pk_mul_f32 v[48:49], v[48:49], v[70:71] op_sel_hi:[1,0]
	v_pk_mul_f32 v[42:43], v[42:43], v[70:71] op_sel_hi:[1,0]
	v_pk_mul_f32 v[44:45], v[44:45], v[70:71] op_sel_hi:[1,0]
	v_pk_mul_f32 v[38:39], v[38:39], v[70:71] op_sel_hi:[1,0]
	v_pk_mul_f32 v[26:27], v[40:41], v[70:71] op_sel_hi:[1,0]
	v_cvt_pk_bf16_f32 v28, v28, v29
	v_cvt_pk_bf16_f32 v29, v50, v51
	v_cvt_pk_bf16_f32 v40, v46, v47
	v_cvt_pk_bf16_f32 v41, v48, v49
	v_cvt_pk_bf16_f32 v42, v42, v43
	v_cvt_pk_bf16_f32 v43, v44, v45
	v_cvt_pk_bf16_f32 v38, v38, v39
	v_cvt_pk_bf16_f32 v39, v26, v27
	global_store_dwordx2 v[152:153], v[28:29], off offset:128
	global_store_dwordx2 v[152:153], v[40:41], off offset:160
	global_store_dwordx2 v[152:153], v[42:43], off offset:192
	global_store_dwordx2 v[152:153], v[38:39], off offset:224
	v_pk_mul_f32 v[28:29], v[34:35], v[72:73] op_sel_hi:[1,0]
	v_pk_mul_f32 v[34:35], v[36:37], v[72:73] op_sel_hi:[1,0]
	v_pk_mul_f32 v[30:31], v[30:31], v[72:73] op_sel_hi:[1,0]
	v_pk_mul_f32 v[32:33], v[32:33], v[72:73] op_sel_hi:[1,0]
	v_pk_mul_f32 v[22:23], v[22:23], v[72:73] op_sel_hi:[1,0]
	v_pk_mul_f32 v[24:25], v[24:25], v[72:73] op_sel_hi:[1,0]
	v_pk_mul_f32 v[18:19], v[18:19], v[72:73] op_sel_hi:[1,0]
	v_pk_mul_f32 v[20:21], v[20:21], v[72:73] op_sel_hi:[1,0]
	v_cvt_pk_bf16_f32 v26, v28, v29
	v_cvt_pk_bf16_f32 v27, v34, v35
	v_cvt_pk_bf16_f32 v28, v30, v31
	v_cvt_pk_bf16_f32 v29, v32, v33
	v_cvt_pk_bf16_f32 v22, v22, v23
	v_cvt_pk_bf16_f32 v23, v24, v25
	v_cvt_pk_bf16_f32 v18, v18, v19
	v_cvt_pk_bf16_f32 v19, v20, v21
	global_store_dwordx2 v[152:153], v[26:27], off offset:256
	global_store_dwordx2 v[152:153], v[28:29], off offset:288
	global_store_dwordx2 v[152:153], v[22:23], off offset:320
	global_store_dwordx2 v[152:153], v[18:19], off offset:352
	v_lshl_add_u32 v33, v67, 2, v172
	v_pk_mul_f32 v[14:15], v[14:15], v[74:75] op_sel_hi:[1,0]
	v_pk_mul_f32 v[16:17], v[16:17], v[74:75] op_sel_hi:[1,0]
	v_pk_mul_f32 v[10:11], v[10:11], v[74:75] op_sel_hi:[1,0]
	v_pk_mul_f32 v[12:13], v[12:13], v[74:75] op_sel_hi:[1,0]
	v_pk_mul_f32 v[6:7], v[6:7], v[74:75] op_sel_hi:[1,0]
	v_pk_mul_f32 v[8:9], v[8:9], v[74:75] op_sel_hi:[1,0]
	v_pk_mul_f32 v[2:3], v[2:3], v[74:75] op_sel_hi:[1,0]
	v_pk_mul_f32 v[4:5], v[4:5], v[74:75] op_sel_hi:[1,0]
	v_cvt_pk_bf16_f32 v14, v14, v15
	v_cvt_pk_bf16_f32 v15, v16, v17
	v_cvt_pk_bf16_f32 v10, v10, v11
	v_cvt_pk_bf16_f32 v11, v12, v13
	v_cvt_pk_bf16_f32 v6, v6, v7
	v_cvt_pk_bf16_f32 v7, v8, v9
	v_cvt_pk_bf16_f32 v2, v2, v3
	v_cvt_pk_bf16_f32 v3, v4, v5
	global_store_dwordx2 v[152:153], v[14:15], off offset:384
	global_store_dwordx2 v[152:153], v[10:11], off offset:416
	global_store_dwordx2 v[152:153], v[6:7], off offset:448
	global_store_dwordx2 v[152:153], v[2:3], off offset:480
	s_waitcnt lgkmcnt(0)
	ds_read_b32 v34, v33 offset:8192
	v_mov_b32_e32 v2, -1.0
	v_mov_b32_e32 v3, -1.0
	s_cbranch_scc0 .LBB0_1236
	ds_read_b32 v3, v33 offset:8196
	s_cmpk_lt_u32 s1, 0xc0
	s_cselect_b64 vcc, -1, 0
	v_cndmask_b32_e32 v4, 0, v181, vcc
	s_waitcnt lgkmcnt(0)
	v_add_f32_e32 v3, v4, v3

.LBB0_1274:
	s_xor_b64 s[12:13], s[14:15], -1
	s_and_b64 s[18:19], s[6:7], s[8:9]
	s_cmp_lg_u64 s[18:19], 0
	s_cselect_b64 s[20:21], -1, 0
	v_cndmask_b32_e64 v1, 0, 1, s[20:21]
	s_mov_b64 s[6:7], -1
	s_and_b64 vcc, exec, s[4:5]
	v_cmp_ne_u32_e64 s[4:5], 1, v1
	s_cbranch_vccz .LBB0_1291
	s_and_b64 vcc, exec, s[4:5]
	s_cbranch_vccnz .LBB0_1289
	s_ff1_i32_b64 s24, s[18:19]
	s_add_u32 s6, s18, -1
	s_addc_u32 s7, s19, -1
	s_lshl_b32 s74, s24, 13
	v_lshl_add_u64 v[2:3], v[156:157], 0, s[74:75]
	global_load_dwordx4 v[136:139], v[2:3], off
	global_load_dwordx4 v[140:143], v[2:3], off offset:64
	global_load_dwordx4 v[144:147], v[2:3], off offset:1024
	global_load_dwordx4 v[132:135], v[2:3], off offset:1088
	ds_read_b128 v[72:75], v208
	ds_read_b128 v[76:79], v208 offset:1024
	ds_read_b128 v[80:83], v208 offset:2048
	ds_read_b128 v[84:87], v208 offset:3072
	ds_read_b128 v[88:91], v208 offset:4096
	ds_read_b128 v[92:95], v208 offset:5120
	ds_read_b128 v[96:99], v208 offset:7168
	v_mov_b32_e32 v2, v0
	v_mov_b32_e32 v3, v0
	v_mov_b32_e32 v1, v0
	v_mov_b64_e32 v[10:11], v[2:3]
	v_mov_b64_e32 v[14:15], v[2:3]
	v_mov_b64_e32 v[18:19], v[2:3]
	v_mov_b64_e32 v[22:23], v[2:3]
	v_mov_b64_e32 v[26:27], v[2:3]
	v_mov_b64_e32 v[30:31], v[2:3]
	v_mov_b64_e32 v[34:35], v[2:3]
	v_mov_b64_e32 v[38:39], v[2:3]
	v_mov_b64_e32 v[42:43], v[2:3]
	v_mov_b64_e32 v[46:47], v[2:3]
	v_mov_b64_e32 v[50:51], v[2:3]
	v_mov_b64_e32 v[54:55], v[2:3]
	v_mov_b64_e32 v[58:59], v[2:3]
	v_mov_b64_e32 v[62:63], v[2:3]
	v_mov_b64_e32 v[66:67], v[2:3]
	v_mov_b64_e32 v[70:71], v[2:3]
	s_and_b64 s[20:21], s[6:7], s[18:19]
	v_mov_b32_e32 v218, 0xefa18f08
	v_mov_b32_e32 v215, 0
	v_mov_b64_e32 v[8:9], v[0:1]
	v_mov_b64_e32 v[12:13], v[0:1]
	v_mov_b64_e32 v[16:17], v[0:1]
	v_mov_b64_e32 v[20:21], v[0:1]
	v_mov_b64_e32 v[24:25], v[0:1]
	v_mov_b64_e32 v[28:29], v[0:1]
	v_mov_b64_e32 v[32:33], v[0:1]
	v_mov_b64_e32 v[36:37], v[0:1]
	v_mov_b32_e32 v216, 0
	v_mov_b32_e32 v219, 0xefa18f08
	v_mov_b64_e32 v[40:41], v[0:1]
	v_mov_b64_e32 v[44:45], v[0:1]
	v_mov_b64_e32 v[48:49], v[0:1]
	v_mov_b64_e32 v[52:53], v[0:1]
	v_mov_b32_e32 v217, 0
	v_mov_b32_e32 v220, 0xefa18f08
	v_mov_b64_e32 v[56:57], v[0:1]
	v_mov_b64_e32 v[60:61], v[0:1]
	v_mov_b64_e32 v[64:65], v[0:1]
	v_mov_b64_e32 v[68:69], v[0:1]
	v_mov_b32_e32 v1, 0
	v_mov_b32_e32 v2, 0xefa18f08
	s_waitcnt vmcnt(0)

.LBB0_1279:
	s_lshl_b32 s6, s24, 5
	v_or_b32_e32 v227, s6, v150
	v_add_u32_e32 v3, 0x200, v227
	v_cmp_le_u32_e32 vcc, v227, v207
	v_cmp_gt_u32_e64 s[6:7], v3, v207
	s_and_b64 s[6:7], vcc, s[6:7]
	v_add_u32_e32 v168, 0x201, v227
	v_cndmask_b32_e64 v3, v180, 0, s[6:7]
	v_cmp_lt_u32_e32 vcc, v227, v207
	v_cmp_gt_u32_e64 s[6:7], v168, v207
	v_or_b32_e32 v168, 2, v227
	s_and_b64 s[6:7], vcc, s[6:7]
	v_cmp_le_u32_e32 vcc, v168, v207
	v_add_u32_e32 v168, 0x202, v227
	v_cndmask_b32_e64 v221, v180, 0, s[6:7]
	v_cmp_gt_u32_e64 s[6:7], v168, v207
	v_or_b32_e32 v168, 3, v227
	s_and_b64 s[6:7], vcc, s[6:7]
	v_cmp_le_u32_e32 vcc, v168, v207
	v_add_u32_e32 v168, 0x203, v227
	v_cndmask_b32_e64 v222, v180, 0, s[6:7]
	v_cmp_gt_u32_e64 s[6:7], v168, v207
	v_or_b32_e32 v168, 4, v227
	s_and_b64 s[6:7], vcc, s[6:7]
	v_cmp_le_u32_e32 vcc, v168, v207
	v_add_u32_e32 v168, 0x204, v227
	v_cndmask_b32_e64 v223, v180, 0, s[6:7]
	v_cmp_gt_u32_e64 s[6:7], v168, v207
	v_or_b32_e32 v168, 5, v227
	s_and_b64 s[6:7], vcc, s[6:7]
	v_cmp_le_u32_e32 vcc, v168, v207
	v_add_u32_e32 v168, 0x205, v227
	v_cndmask_b32_e64 v224, v180, 0, s[6:7]
	v_cmp_gt_u32_e64 s[6:7], v168, v207
	v_or_b32_e32 v168, 6, v227
	s_and_b64 s[6:7], vcc, s[6:7]
	v_cmp_le_u32_e32 vcc, v168, v207
	s_waitcnt lgkmcnt(6)
	v_mfma_f32_16x16x32_bf16 v[168:171], v[136:139], v[72:75], 0
	v_add_u32_e32 v226, 0x206, v227
	v_cndmask_b32_e64 v225, v180, 0, s[6:7]
	v_cmp_gt_u32_e64 s[6:7], v226, v207
	v_mfma_f32_16x16x32_bf16 v[228:231], v[144:147], v[72:75], 0
	v_or_b32_e32 v232, 7, v227
	s_and_b64 s[6:7], vcc, s[6:7]
	v_cmp_le_u32_e32 vcc, v232, v207
	s_waitcnt lgkmcnt(5)
	v_mfma_f32_16x16x32_bf16 v[168:171], v[140:143], v[76:79], v[168:171]
	v_add_u32_e32 v227, 0x207, v227
	v_cndmask_b32_e64 v226, v180, 0, s[6:7]
	v_cmp_gt_u32_e64 s[6:7], v227, v207
	v_mfma_f32_16x16x32_bf16 v[232:235], v[132:135], v[76:79], v[228:231]
	s_and_b64 s[6:7], vcc, s[6:7]
	v_cndmask_b32_e64 v227, v180, 0, s[6:7]
	s_nop 0
	v_fmamk_f32 v228, v168, 0x3e38aa3b, v3
	v_fmamk_f32 v229, v169, 0x3e38aa3b, v221
	v_max3_f32 v168, v228, s63, v229
	v_fmamk_f32 v230, v170, 0x3e38aa3b, v222
	v_fmamk_f32 v231, v171, 0x3e38aa3b, v223
	v_max3_f32 v168, v168, v230, v231
	v_fmamk_f32 v232, v232, 0x3e38aa3b, v224
	v_fmamk_f32 v233, v233, 0x3e38aa3b, v225
	v_max3_f32 v168, v168, v232, v233
	v_fmamk_f32 v234, v234, 0x3e38aa3b, v226
	v_fmamk_f32 v235, v235, 0x3e38aa3b, v227
	v_max3_f32 v236, v168, v234, v235
	v_cmp_gt_f32_e32 vcc, v236, v2
	s_cbranch_vccz .LBB0_1281
	ds_bpermute_b32 v168, v209, v236
	v_max_f32_e32 v169, v236, v236
	s_waitcnt lgkmcnt(0)
	v_max_f32_e32 v168, v168, v168
	v_max_f32_e32 v168, v169, v168
	ds_bpermute_b32 v169, v210, v168
	s_waitcnt lgkmcnt(0)
	v_max3_f32 v168, v2, v168, v169
	v_sub_f32_e32 v2, v2, v168
	v_exp_f32_e32 v2, v2
	s_nop 0
	v_mul_f32_e32 v1, v1, v2
	v_pk_mul_f32 v[70:71], v[70:71], v[2:3] op_sel_hi:[1,0]
	v_pk_mul_f32 v[68:69], v[68:69], v[2:3] op_sel_hi:[1,0]
	v_pk_mul_f32 v[66:67], v[66:67], v[2:3] op_sel_hi:[1,0]
	v_pk_mul_f32 v[64:65], v[64:65], v[2:3] op_sel_hi:[1,0]
	v_pk_mul_f32 v[62:63], v[62:63], v[2:3] op_sel_hi:[1,0]
	v_pk_mul_f32 v[60:61], v[60:61], v[2:3] op_sel_hi:[1,0]
	v_pk_mul_f32 v[58:59], v[58:59], v[2:3] op_sel_hi:[1,0]
	v_pk_mul_f32 v[56:57], v[56:57], v[2:3] op_sel_hi:[1,0]
	v_mov_b32_e32 v2, v168

.LBB0_1291:
	s_andn2_b64 vcc, exec, s[6:7]
	s_cbranch_vccnz .LBB0_1307
	s_and_b64 vcc, exec, s[4:5]
	s_cbranch_vccnz .LBB0_1306
	s_ff1_i32_b64 s20, s[18:19]
	s_add_u32 s4, s18, -1
	s_addc_u32 s5, s19, -1
	s_lshl_b32 s74, s20, 13
	v_lshl_add_u64 v[2:3], v[160:161], 0, s[74:75]
	global_load_dwordx4 v[136:139], v[2:3], off
	global_load_dwordx4 v[140:143], v[2:3], off offset:64
	global_load_dwordx4 v[144:147], v[2:3], off offset:1024
	global_load_dwordx4 v[132:135], v[2:3], off offset:1088
	ds_read_b128 v[72:75], v208
	ds_read_b128 v[76:79], v208 offset:1024
	ds_read_b128 v[80:83], v208 offset:2048
	ds_read_b128 v[84:87], v208 offset:3072
	ds_read_b128 v[88:91], v208 offset:4096
	ds_read_b128 v[92:95], v208 offset:5120
	ds_read_b128 v[96:99], v208 offset:7168
	v_mov_b32_e32 v2, v0
	v_mov_b32_e32 v3, v0
	v_mov_b32_e32 v1, v0
	v_mov_b64_e32 v[10:11], v[2:3]
	v_mov_b64_e32 v[14:15], v[2:3]
	v_mov_b64_e32 v[18:19], v[2:3]
	v_mov_b64_e32 v[22:23], v[2:3]
	v_mov_b64_e32 v[26:27], v[2:3]
	v_mov_b64_e32 v[30:31], v[2:3]
	v_mov_b64_e32 v[34:35], v[2:3]
	v_mov_b64_e32 v[38:39], v[2:3]
	v_mov_b64_e32 v[42:43], v[2:3]
	v_mov_b64_e32 v[46:47], v[2:3]
	v_mov_b64_e32 v[50:51], v[2:3]
	v_mov_b64_e32 v[54:55], v[2:3]
	v_mov_b64_e32 v[58:59], v[2:3]
	v_mov_b64_e32 v[62:63], v[2:3]
	v_mov_b64_e32 v[66:67], v[2:3]
	v_mov_b64_e32 v[70:71], v[2:3]
	s_and_b64 s[6:7], s[4:5], s[18:19]
	v_mov_b32_e32 v218, 0xefa18f08
	v_mov_b32_e32 v215, 0
	v_mov_b64_e32 v[8:9], v[0:1]
	v_mov_b64_e32 v[12:13], v[0:1]
	v_mov_b64_e32 v[16:17], v[0:1]
	v_mov_b64_e32 v[20:21], v[0:1]
	v_mov_b64_e32 v[24:25], v[0:1]
	v_mov_b64_e32 v[28:29], v[0:1]
	v_mov_b64_e32 v[32:33], v[0:1]
	v_mov_b64_e32 v[36:37], v[0:1]
	v_mov_b32_e32 v216, 0
	v_mov_b32_e32 v219, 0xefa18f08
	v_mov_b64_e32 v[40:41], v[0:1]
	v_mov_b64_e32 v[44:45], v[0:1]
	v_mov_b64_e32 v[48:49], v[0:1]
	v_mov_b64_e32 v[52:53], v[0:1]
	v_mov_b32_e32 v217, 0
	v_mov_b32_e32 v220, 0xefa18f08
	v_mov_b64_e32 v[56:57], v[0:1]
	v_mov_b64_e32 v[60:61], v[0:1]
	v_mov_b64_e32 v[64:65], v[0:1]
	v_mov_b64_e32 v[68:69], v[0:1]
	v_mov_b32_e32 v1, 0
	v_mov_b32_e32 v2, 0xefa18f08
	s_waitcnt vmcnt(0)

.LBB0_1296:
	s_lshl_b32 s4, s20, 5
	v_or_b32_e32 v168, s4, v150
	s_lshr_b32 s4, s20, 1
	v_lshrrev_b32_e32 v3, s4, v151
	v_and_b32_e32 v3, 1, v3
	v_cmp_eq_u32_e32 vcc, 1, v3
	v_cmp_le_u32_e64 s[4:5], v168, v207
	s_and_b64 s[4:5], vcc, s[4:5]
	v_or_b32_e32 v169, 2, v168
	v_cndmask_b32_e64 v3, v180, 0, s[4:5]
	v_cmp_lt_u32_e64 s[4:5], v168, v207
	s_and_b64 s[4:5], vcc, s[4:5]
	s_waitcnt lgkmcnt(6)
	v_mfma_f32_16x16x32_bf16 v[228:231], v[136:139], v[72:75], 0
	v_cndmask_b32_e64 v221, v180, 0, s[4:5]
	v_cmp_le_u32_e64 s[4:5], v169, v207
	s_and_b64 s[4:5], vcc, s[4:5]
	v_or_b32_e32 v169, 3, v168
	v_cndmask_b32_e64 v222, v180, 0, s[4:5]
	v_cmp_le_u32_e64 s[4:5], v169, v207
	s_and_b64 s[4:5], vcc, s[4:5]
	v_or_b32_e32 v169, 4, v168
	v_cndmask_b32_e64 v223, v180, 0, s[4:5]
	v_cmp_le_u32_e64 s[4:5], v169, v207
	v_mfma_f32_16x16x32_bf16 v[232:235], v[144:147], v[72:75], 0
	s_and_b64 s[4:5], vcc, s[4:5]
	v_or_b32_e32 v169, 5, v168
	v_cndmask_b32_e64 v224, v180, 0, s[4:5]
	v_cmp_le_u32_e64 s[4:5], v169, v207
	s_waitcnt lgkmcnt(5)
	v_mfma_f32_16x16x32_bf16 v[228:231], v[140:143], v[76:79], v[228:231]
	s_and_b64 s[4:5], vcc, s[4:5]
	v_or_b32_e32 v169, 6, v168
	v_cndmask_b32_e64 v225, v180, 0, s[4:5]
	v_cmp_le_u32_e64 s[4:5], v169, v207
	v_mfma_f32_16x16x32_bf16 v[232:235], v[132:135], v[76:79], v[232:235]
	s_and_b64 s[4:5], vcc, s[4:5]
	v_or_b32_e32 v168, 7, v168
	v_cndmask_b32_e64 v226, v180, 0, s[4:5]
	v_cmp_le_u32_e64 s[4:5], v168, v207
	v_fmamk_f32 v228, v228, 0x3e38aa3b, v3
	v_fmamk_f32 v229, v229, 0x3e38aa3b, v221
	s_and_b64 s[4:5], vcc, s[4:5]
	v_max3_f32 v168, v228, s63, v229
	v_fmamk_f32 v230, v230, 0x3e38aa3b, v222
	v_fmamk_f32 v231, v231, 0x3e38aa3b, v223
	v_cndmask_b32_e64 v227, v180, 0, s[4:5]
	v_max3_f32 v168, v168, v230, v231
	v_fmamk_f32 v232, v232, 0x3e38aa3b, v224
	v_fmamk_f32 v233, v233, 0x3e38aa3b, v225
	v_max3_f32 v168, v168, v232, v233
	v_fmamk_f32 v234, v234, 0x3e38aa3b, v226
	v_fmamk_f32 v235, v235, 0x3e38aa3b, v227
	v_max3_f32 v236, v168, v234, v235
	v_cmp_gt_f32_e32 vcc, v236, v2
	s_cbranch_vccz .LBB0_1298
	ds_bpermute_b32 v168, v209, v236
	v_max_f32_e32 v169, v236, v236
	s_waitcnt lgkmcnt(0)
	v_max_f32_e32 v168, v168, v168
	v_max_f32_e32 v168, v169, v168
	ds_bpermute_b32 v169, v210, v168
	s_waitcnt lgkmcnt(0)
	v_max3_f32 v168, v2, v168, v169
	v_sub_f32_e32 v2, v2, v168
	v_exp_f32_e32 v2, v2
	s_nop 0
	v_mul_f32_e32 v1, v1, v2
	v_pk_mul_f32 v[70:71], v[70:71], v[2:3] op_sel_hi:[1,0]
	v_pk_mul_f32 v[68:69], v[68:69], v[2:3] op_sel_hi:[1,0]
	v_pk_mul_f32 v[66:67], v[66:67], v[2:3] op_sel_hi:[1,0]
	v_pk_mul_f32 v[64:65], v[64:65], v[2:3] op_sel_hi:[1,0]
	v_pk_mul_f32 v[62:63], v[62:63], v[2:3] op_sel_hi:[1,0]
	v_pk_mul_f32 v[60:61], v[60:61], v[2:3] op_sel_hi:[1,0]
	v_pk_mul_f32 v[58:59], v[58:59], v[2:3] op_sel_hi:[1,0]
	v_pk_mul_f32 v[56:57], v[56:57], v[2:3] op_sel_hi:[1,0]
	v_mov_b32_e32 v2, v168

.LBB0_1307:
	v_lshl_add_u64 v[2:3], s[16:17], 2, v[154:155]
	global_load_dwordx2 v[80:81], v[152:153], off
	global_load_dwordx2 v[82:83], v[152:153], off offset:32
	global_load_dwordx2 v[84:85], v[152:153], off offset:64
	global_load_dwordx2 v[86:87], v[152:153], off offset:96
	global_load_dwordx2 v[88:89], v[152:153], off offset:128
	global_load_dwordx2 v[90:91], v[152:153], off offset:160
	global_load_dwordx2 v[92:93], v[152:153], off offset:192
	global_load_dwordx2 v[94:95], v[152:153], off offset:224
	global_load_dwordx2 v[96:97], v[152:153], off offset:256
	global_load_dwordx2 v[98:99], v[152:153], off offset:288
	global_load_dwordx2 v[100:101], v[152:153], off offset:320
	global_load_dwordx2 v[102:103], v[152:153], off offset:352
	global_load_dwordx2 v[104:105], v[152:153], off offset:384
	global_load_dwordx2 v[106:107], v[152:153], off offset:416
	global_load_dwordx2 v[108:109], v[152:153], off offset:448
	global_load_dwordx2 v[110:111], v[152:153], off offset:480
	global_load_dword v142, v[2:3], off
	global_load_dword v143, v[2:3], off offset:12
	global_load_dword v144, v[2:3], off offset:24
	global_load_dword v145, v[2:3], off offset:36
	s_andn2_b64 vcc, exec, s[14:15]
	s_cbranch_vccnz .Lnsa_epi_nog
	global_load_dwordx2 v[112:113], v[164:165], off
	global_load_dwordx2 v[114:115], v[164:165], off offset:32
	global_load_dwordx2 v[116:117], v[164:165], off offset:64
	global_load_dwordx2 v[118:119], v[164:165], off offset:96
	global_load_dwordx2 v[120:121], v[164:165], off offset:128
	global_load_dwordx2 v[122:123], v[164:165], off offset:160
	global_load_dwordx2 v[124:125], v[164:165], off offset:192
	global_load_dwordx2 v[126:127], v[164:165], off offset:224
	global_load_dwordx2 v[128:129], v[164:165], off offset:256
	global_load_dwordx2 v[130:131], v[164:165], off offset:288
	global_load_dwordx2 v[132:133], v[164:165], off offset:320
	global_load_dwordx2 v[134:135], v[164:165], off offset:352
	global_load_dwordx2 v[136:137], v[164:165], off offset:384
	global_load_dwordx2 v[138:139], v[164:165], off offset:416
	global_load_dwordx2 v[140:141], v[164:165], off offset:448
.Lnsa_epi_nog:
	ds_bpermute_b32 v74, v209, v1
	v_cndmask_b32_e64 v75, 0, 1, s[14:15]
	s_waitcnt lgkmcnt(0)
	v_add_f32_e32 v1, v1, v74
	ds_bpermute_b32 v74, v210, v1
	s_waitcnt lgkmcnt(0)
	v_add_f32_e32 v1, v1, v74
	v_div_scale_f32 v74, s[4:5], v1, v1, 1.0
	v_rcp_f32_e32 v76, v74
	v_cmp_ne_u32_e64 s[4:5], 1, v75
	v_div_scale_f32 v75, vcc, 1.0, v1, 1.0
	v_fma_f32 v77, -v74, v76, 1.0
	v_fmac_f32_e32 v76, v77, v76
	v_mul_f32_e32 v77, v75, v76
	v_fma_f32 v79, -v74, v77, v75
	v_fmac_f32_e32 v77, v79, v76
	v_fma_f32 v74, -v74, v77, v75
	v_div_fmas_f32 v74, v74, v76, v77
	v_div_fixup_f32 v74, v74, v1, 1.0
	v_cmp_lt_f32_e64 s[6:7], 0, v1
	s_andn2_b64 vcc, exec, s[14:15]
	s_waitcnt vmcnt(0)
	v_and_b32_e32 v75, 0xffff0000, v80
	v_cndmask_b32_e64 v1, 0, v74, s[6:7]
	v_lshlrev_b32_e32 v74, 16, v80
	v_lshlrev_b32_e32 v76, 16, v81
	v_and_b32_e32 v77, 0xffff0000, v81
	v_mul_f32_e32 v72, v142, v1
	v_pk_fma_f32 v[68:69], v[68:69], v[72:73], v[74:75] op_sel_hi:[1,0,1]
	v_pk_fma_f32 v[70:71], v[70:71], v[72:73], v[76:77] op_sel_hi:[1,0,1]
	s_cbranch_vccnz .LBB0_1309
	v_lshlrev_b32_e32 v76, 16, v112
	v_and_b32_e32 v77, 0xffff0000, v112
	v_lshlrev_b32_e32 v74, 16, v113
	v_and_b32_e32 v75, 0xffff0000, v113
	v_pk_mul_f32 v[68:69], v[68:69], v[76:77]
	v_pk_mul_f32 v[70:71], v[70:71], v[74:75]
.LBB0_1309:
	v_cvt_pk_bf16_f32 v68, v68, v69
	v_cvt_pk_bf16_f32 v69, v70, v71
	v_mov_b32_e32 v73, v72
	global_store_dwordx2 v[152:153], v[68:69], off
	s_and_b64 vcc, exec, s[4:5]
	v_lshlrev_b32_e32 v68, 16, v82
	v_and_b32_e32 v69, 0xffff0000, v82
	v_lshlrev_b32_e32 v70, 16, v83
	v_and_b32_e32 v71, 0xffff0000, v83
	v_pk_fma_f32 v[64:65], v[64:65], v[72:73], v[68:69]
	v_pk_fma_f32 v[66:67], v[66:67], v[72:73], v[70:71]
	s_cbranch_vccnz .LBB0_1311
	v_lshlrev_b32_e32 v70, 16, v114
	v_and_b32_e32 v71, 0xffff0000, v114
	v_lshlrev_b32_e32 v68, 16, v115
	v_and_b32_e32 v69, 0xffff0000, v115
	v_pk_mul_f32 v[64:65], v[64:65], v[70:71]
	v_pk_mul_f32 v[66:67], v[66:67], v[68:69]
.LBB0_1311:
	v_cvt_pk_bf16_f32 v64, v64, v65
	v_cvt_pk_bf16_f32 v65, v66, v67
	global_store_dwordx2 v[152:153], v[64:65], off offset:32
	s_and_b64 vcc, exec, s[4:5]
	v_lshlrev_b32_e32 v64, 16, v84
	v_and_b32_e32 v65, 0xffff0000, v84
	v_lshlrev_b32_e32 v66, 16, v85
	v_and_b32_e32 v67, 0xffff0000, v85
	v_pk_fma_f32 v[60:61], v[60:61], v[72:73], v[64:65]
	v_pk_fma_f32 v[62:63], v[62:63], v[72:73], v[66:67]
	s_cbranch_vccnz .LBB0_1313
	v_lshlrev_b32_e32 v66, 16, v116
	v_and_b32_e32 v67, 0xffff0000, v116
	v_lshlrev_b32_e32 v64, 16, v117
	v_and_b32_e32 v65, 0xffff0000, v117
	v_pk_mul_f32 v[60:61], v[60:61], v[66:67]
	v_pk_mul_f32 v[62:63], v[62:63], v[64:65]
.LBB0_1313:
	v_cvt_pk_bf16_f32 v60, v60, v61
	v_cvt_pk_bf16_f32 v61, v62, v63
	global_store_dwordx2 v[152:153], v[60:61], off offset:64
	s_and_b64 vcc, exec, s[4:5]
	v_lshlrev_b32_e32 v60, 16, v86
	v_and_b32_e32 v61, 0xffff0000, v86
	v_lshlrev_b32_e32 v62, 16, v87
	v_and_b32_e32 v63, 0xffff0000, v87
	v_pk_fma_f32 v[56:57], v[56:57], v[72:73], v[60:61]
	v_pk_fma_f32 v[58:59], v[58:59], v[72:73], v[62:63]
	s_cbranch_vccnz .LBB0_1315
	v_lshlrev_b32_e32 v62, 16, v118
	v_and_b32_e32 v63, 0xffff0000, v118
	v_lshlrev_b32_e32 v60, 16, v119
	v_and_b32_e32 v61, 0xffff0000, v119
	v_pk_mul_f32 v[56:57], v[56:57], v[62:63]
	v_pk_mul_f32 v[58:59], v[58:59], v[60:61]
.LBB0_1315:
	v_cvt_pk_bf16_f32 v56, v56, v57
	v_cvt_pk_bf16_f32 v57, v58, v59
	global_store_dwordx2 v[152:153], v[56:57], off offset:96
	ds_bpermute_b32 v56, v209, v217
	s_waitcnt lgkmcnt(0)
	v_add_f32_e32 v56, v217, v56
	ds_bpermute_b32 v57, v210, v56
	s_waitcnt lgkmcnt(0)
	v_add_f32_e32 v56, v56, v57
	v_div_scale_f32 v57, s[6:7], v56, v56, 1.0
	v_rcp_f32_e32 v58, v57
	v_div_scale_f32 v59, vcc, 1.0, v56, 1.0
	v_cmp_lt_f32_e64 s[6:7], 0, v56
	v_fma_f32 v62, -v57, v58, 1.0
	v_fmac_f32_e32 v58, v62, v58
	v_mul_f32_e32 v62, v59, v58
	v_fma_f32 v63, -v57, v62, v59
	v_fmac_f32_e32 v62, v63, v58
	v_fma_f32 v57, -v57, v62, v59
	v_div_fmas_f32 v57, v57, v58, v62
	v_div_fixup_f32 v57, v57, v56, 1.0
	v_cndmask_b32_e64 v56, 0, v57, s[6:7]
	s_and_b64 vcc, exec, s[4:5]
	v_lshlrev_b32_e32 v58, 16, v88
	v_and_b32_e32 v59, 0xffff0000, v88
	v_lshlrev_b32_e32 v60, 16, v89
	v_and_b32_e32 v61, 0xffff0000, v89
	v_mul_f32_e32 v56, v143, v56
	v_pk_fma_f32 v[52:53], v[52:53], v[56:57], v[58:59] op_sel_hi:[1,0,1]
	v_pk_fma_f32 v[54:55], v[54:55], v[56:57], v[60:61] op_sel_hi:[1,0,1]
	s_cbranch_vccnz .LBB0_1317
	v_lshlrev_b32_e32 v60, 16, v120
	v_and_b32_e32 v61, 0xffff0000, v120
	v_lshlrev_b32_e32 v58, 16, v121
	v_and_b32_e32 v59, 0xffff0000, v121
	v_pk_mul_f32 v[52:53], v[52:53], v[60:61]
	v_pk_mul_f32 v[54:55], v[54:55], v[58:59]
.LBB0_1317:
	v_cvt_pk_bf16_f32 v52, v52, v53
	v_cvt_pk_bf16_f32 v53, v54, v55
	v_mov_b32_e32 v57, v56
	global_store_dwordx2 v[152:153], v[52:53], off offset:128
	s_and_b64 vcc, exec, s[4:5]
	v_lshlrev_b32_e32 v52, 16, v90
	v_and_b32_e32 v53, 0xffff0000, v90
	v_lshlrev_b32_e32 v54, 16, v91
	v_and_b32_e32 v55, 0xffff0000, v91
	v_pk_fma_f32 v[48:49], v[48:49], v[56:57], v[52:53]
	v_pk_fma_f32 v[50:51], v[50:51], v[56:57], v[54:55]
	s_cbranch_vccnz .LBB0_1319
	v_lshlrev_b32_e32 v54, 16, v122
	v_and_b32_e32 v55, 0xffff0000, v122
	v_lshlrev_b32_e32 v52, 16, v123
	v_and_b32_e32 v53, 0xffff0000, v123
	v_pk_mul_f32 v[48:49], v[48:49], v[54:55]
	v_pk_mul_f32 v[50:51], v[50:51], v[52:53]
.LBB0_1319:
	v_cvt_pk_bf16_f32 v48, v48, v49
	v_cvt_pk_bf16_f32 v49, v50, v51
	global_store_dwordx2 v[152:153], v[48:49], off offset:160
	s_and_b64 vcc, exec, s[4:5]
	v_lshlrev_b32_e32 v48, 16, v92
	v_and_b32_e32 v49, 0xffff0000, v92
	v_lshlrev_b32_e32 v50, 16, v93
	v_and_b32_e32 v51, 0xffff0000, v93
	v_pk_fma_f32 v[44:45], v[44:45], v[56:57], v[48:49]
	v_pk_fma_f32 v[46:47], v[46:47], v[56:57], v[50:51]
	s_cbranch_vccnz .LBB0_1321
	v_lshlrev_b32_e32 v50, 16, v124
	v_and_b32_e32 v51, 0xffff0000, v124
	v_lshlrev_b32_e32 v48, 16, v125
	v_and_b32_e32 v49, 0xffff0000, v125
	v_pk_mul_f32 v[44:45], v[44:45], v[50:51]
	v_pk_mul_f32 v[46:47], v[46:47], v[48:49]
.LBB0_1321:
	v_cvt_pk_bf16_f32 v44, v44, v45
	v_cvt_pk_bf16_f32 v45, v46, v47
	global_store_dwordx2 v[152:153], v[44:45], off offset:192
	s_and_b64 vcc, exec, s[4:5]
	v_lshlrev_b32_e32 v44, 16, v94
	v_and_b32_e32 v45, 0xffff0000, v94
	v_lshlrev_b32_e32 v46, 16, v95
	v_and_b32_e32 v47, 0xffff0000, v95
	v_pk_fma_f32 v[40:41], v[40:41], v[56:57], v[44:45]
	v_pk_fma_f32 v[42:43], v[42:43], v[56:57], v[46:47]
	s_cbranch_vccnz .LBB0_1323
	v_lshlrev_b32_e32 v46, 16, v126
	v_and_b32_e32 v47, 0xffff0000, v126
	v_lshlrev_b32_e32 v44, 16, v127
	v_and_b32_e32 v45, 0xffff0000, v127
	v_pk_mul_f32 v[40:41], v[40:41], v[46:47]
	v_pk_mul_f32 v[42:43], v[42:43], v[44:45]
.LBB0_1323:
	v_cvt_pk_bf16_f32 v40, v40, v41
	v_cvt_pk_bf16_f32 v41, v42, v43
	global_store_dwordx2 v[152:153], v[40:41], off offset:224
	ds_bpermute_b32 v40, v209, v216
	s_waitcnt lgkmcnt(0)
	v_add_f32_e32 v40, v216, v40
	ds_bpermute_b32 v41, v210, v40
	s_waitcnt lgkmcnt(0)
	v_add_f32_e32 v40, v40, v41
	v_div_scale_f32 v41, s[6:7], v40, v40, 1.0
	v_rcp_f32_e32 v42, v41
	v_div_scale_f32 v43, vcc, 1.0, v40, 1.0
	v_cmp_lt_f32_e64 s[6:7], 0, v40
	v_fma_f32 v46, -v41, v42, 1.0
	v_fmac_f32_e32 v42, v46, v42
	v_mul_f32_e32 v46, v43, v42
	v_fma_f32 v47, -v41, v46, v43
	v_fmac_f32_e32 v46, v47, v42
	v_fma_f32 v41, -v41, v46, v43
	v_div_fmas_f32 v41, v41, v42, v46
	v_div_fixup_f32 v41, v41, v40, 1.0
	v_cndmask_b32_e64 v40, 0, v41, s[6:7]
	s_and_b64 vcc, exec, s[4:5]
	v_lshlrev_b32_e32 v42, 16, v96
	v_and_b32_e32 v43, 0xffff0000, v96
	v_lshlrev_b32_e32 v44, 16, v97
	v_and_b32_e32 v45, 0xffff0000, v97
	v_mul_f32_e32 v40, v144, v40
	v_pk_fma_f32 v[36:37], v[36:37], v[40:41], v[42:43] op_sel_hi:[1,0,1]
	v_pk_fma_f32 v[38:39], v[38:39], v[40:41], v[44:45] op_sel_hi:[1,0,1]
	s_cbranch_vccnz .LBB0_1325
	v_lshlrev_b32_e32 v44, 16, v128
	v_and_b32_e32 v45, 0xffff0000, v128
	v_lshlrev_b32_e32 v42, 16, v129
	v_and_b32_e32 v43, 0xffff0000, v129
	v_pk_mul_f32 v[36:37], v[36:37], v[44:45]
	v_pk_mul_f32 v[38:39], v[38:39], v[42:43]
.LBB0_1325:
	v_cvt_pk_bf16_f32 v36, v36, v37
	v_cvt_pk_bf16_f32 v37, v38, v39
	v_mov_b32_e32 v41, v40
	global_store_dwordx2 v[152:153], v[36:37], off offset:256
	s_and_b64 vcc, exec, s[4:5]
	v_lshlrev_b32_e32 v36, 16, v98
	v_and_b32_e32 v37, 0xffff0000, v98
	v_lshlrev_b32_e32 v38, 16, v99
	v_and_b32_e32 v39, 0xffff0000, v99
	v_pk_fma_f32 v[32:33], v[32:33], v[40:41], v[36:37]
	v_pk_fma_f32 v[34:35], v[34:35], v[40:41], v[38:39]
	s_cbranch_vccnz .LBB0_1327
	v_lshlrev_b32_e32 v38, 16, v130
	v_and_b32_e32 v39, 0xffff0000, v130
	v_lshlrev_b32_e32 v36, 16, v131
	v_and_b32_e32 v37, 0xffff0000, v131
	v_pk_mul_f32 v[32:33], v[32:33], v[38:39]
	v_pk_mul_f32 v[34:35], v[34:35], v[36:37]
.LBB0_1327:
	v_cvt_pk_bf16_f32 v32, v32, v33
	v_cvt_pk_bf16_f32 v33, v34, v35
	global_store_dwordx2 v[152:153], v[32:33], off offset:288
	s_and_b64 vcc, exec, s[4:5]
	v_lshlrev_b32_e32 v32, 16, v100
	v_and_b32_e32 v33, 0xffff0000, v100
	v_lshlrev_b32_e32 v34, 16, v101
	v_and_b32_e32 v35, 0xffff0000, v101
	v_pk_fma_f32 v[28:29], v[28:29], v[40:41], v[32:33]
	v_pk_fma_f32 v[30:31], v[30:31], v[40:41], v[34:35]
	s_cbranch_vccnz .LBB0_1329
	v_lshlrev_b32_e32 v34, 16, v132
	v_and_b32_e32 v35, 0xffff0000, v132
	v_lshlrev_b32_e32 v32, 16, v133
	v_and_b32_e32 v33, 0xffff0000, v133
	v_pk_mul_f32 v[28:29], v[28:29], v[34:35]
	v_pk_mul_f32 v[30:31], v[30:31], v[32:33]
.LBB0_1329:
	v_cvt_pk_bf16_f32 v28, v28, v29
	v_cvt_pk_bf16_f32 v29, v30, v31
	global_store_dwordx2 v[152:153], v[28:29], off offset:320
	s_and_b64 vcc, exec, s[4:5]
	v_lshlrev_b32_e32 v28, 16, v102
	v_and_b32_e32 v29, 0xffff0000, v102
	v_lshlrev_b32_e32 v30, 16, v103
	v_and_b32_e32 v31, 0xffff0000, v103
	v_pk_fma_f32 v[24:25], v[24:25], v[40:41], v[28:29]
	v_pk_fma_f32 v[26:27], v[26:27], v[40:41], v[30:31]
	s_cbranch_vccnz .LBB0_1331
	v_lshlrev_b32_e32 v30, 16, v134
	v_and_b32_e32 v31, 0xffff0000, v134
	v_lshlrev_b32_e32 v28, 16, v135
	v_and_b32_e32 v29, 0xffff0000, v135
	v_pk_mul_f32 v[24:25], v[24:25], v[30:31]
	v_pk_mul_f32 v[26:27], v[26:27], v[28:29]
.LBB0_1331:
	v_cvt_pk_bf16_f32 v24, v24, v25
	v_cvt_pk_bf16_f32 v25, v26, v27
	global_store_dwordx2 v[152:153], v[24:25], off offset:352
	ds_bpermute_b32 v2, v209, v215
	s_waitcnt lgkmcnt(0)
	v_add_f32_e32 v2, v215, v2
	ds_bpermute_b32 v3, v210, v2
	s_waitcnt lgkmcnt(0)
	v_add_f32_e32 v2, v2, v3
	v_div_scale_f32 v3, s[6:7], v2, v2, 1.0
	v_rcp_f32_e32 v24, v3
	v_div_scale_f32 v25, vcc, 1.0, v2, 1.0
	v_cmp_lt_f32_e64 s[6:7], 0, v2
	v_fma_f32 v26, -v3, v24, 1.0
	v_fmac_f32_e32 v24, v26, v24
	v_mul_f32_e32 v26, v25, v24
	v_fma_f32 v27, -v3, v26, v25
	v_fmac_f32_e32 v26, v27, v24
	v_fma_f32 v3, -v3, v26, v25
	v_div_fmas_f32 v3, v3, v24, v26
	v_div_fixup_f32 v3, v3, v2, 1.0
	v_cndmask_b32_e64 v2, 0, v3, s[6:7]
	s_and_b64 vcc, exec, s[4:5]
	v_lshlrev_b32_e32 v24, 16, v104
	v_and_b32_e32 v25, 0xffff0000, v104
	v_lshlrev_b32_e32 v26, 16, v105
	v_and_b32_e32 v27, 0xffff0000, v105
	v_mul_f32_e32 v2, v145, v2
	v_pk_fma_f32 v[20:21], v[20:21], v[2:3], v[24:25] op_sel_hi:[1,0,1]
	v_pk_fma_f32 v[22:23], v[22:23], v[2:3], v[26:27] op_sel_hi:[1,0,1]
	s_cbranch_vccnz .LBB0_1333
	v_lshlrev_b32_e32 v26, 16, v136
	v_and_b32_e32 v27, 0xffff0000, v136
	v_lshlrev_b32_e32 v24, 16, v137
	v_and_b32_e32 v25, 0xffff0000, v137
	v_pk_mul_f32 v[20:21], v[20:21], v[26:27]
	v_pk_mul_f32 v[22:23], v[22:23], v[24:25]
.LBB0_1333:
	v_cvt_pk_bf16_f32 v20, v20, v21
	v_cvt_pk_bf16_f32 v21, v22, v23
	v_mov_b32_e32 v3, v2
	global_store_dwordx2 v[152:153], v[20:21], off offset:384
	s_and_b64 vcc, exec, s[4:5]
	v_lshlrev_b32_e32 v20, 16, v106
	v_and_b32_e32 v21, 0xffff0000, v106
	v_lshlrev_b32_e32 v22, 16, v107
	v_and_b32_e32 v23, 0xffff0000, v107
	v_pk_fma_f32 v[16:17], v[16:17], v[2:3], v[20:21]
	v_pk_fma_f32 v[18:19], v[18:19], v[2:3], v[22:23]
	s_cbranch_vccnz .LBB0_1335
	v_lshlrev_b32_e32 v22, 16, v138
	v_and_b32_e32 v23, 0xffff0000, v138
	v_lshlrev_b32_e32 v20, 16, v139
	v_and_b32_e32 v21, 0xffff0000, v139
	v_pk_mul_f32 v[16:17], v[16:17], v[22:23]
	v_pk_mul_f32 v[18:19], v[18:19], v[20:21]
.LBB0_1335:
	v_cvt_pk_bf16_f32 v16, v16, v17
	v_cvt_pk_bf16_f32 v17, v18, v19
	global_store_dwordx2 v[152:153], v[16:17], off offset:416
	s_and_b64 vcc, exec, s[4:5]
	v_lshlrev_b32_e32 v16, 16, v108
	v_and_b32_e32 v17, 0xffff0000, v108
	v_lshlrev_b32_e32 v18, 16, v109
	v_and_b32_e32 v19, 0xffff0000, v109
	v_pk_fma_f32 v[12:13], v[12:13], v[2:3], v[16:17]
	v_pk_fma_f32 v[14:15], v[14:15], v[2:3], v[18:19]
	s_cbranch_vccnz .LBB0_1337
	v_lshlrev_b32_e32 v18, 16, v140
	v_and_b32_e32 v19, 0xffff0000, v140
	v_lshlrev_b32_e32 v16, 16, v141
	v_and_b32_e32 v17, 0xffff0000, v141
	v_pk_mul_f32 v[12:13], v[12:13], v[18:19]
	v_pk_mul_f32 v[14:15], v[14:15], v[16:17]
.LBB0_1337:
	v_cvt_pk_bf16_f32 v12, v12, v13
	v_cvt_pk_bf16_f32 v13, v14, v15
	global_store_dwordx2 v[152:153], v[12:13], off offset:448
	s_mov_b64 s[14:15], -1
	s_and_b64 vcc, exec, s[12:13]
	s_mov_b64 s[4:5], -1
	v_lshlrev_b32_e32 v12, 16, v110
	v_and_b32_e32 v13, 0xffff0000, v110
	v_lshlrev_b32_e32 v14, 16, v111
	v_and_b32_e32 v15, 0xffff0000, v111
	v_pk_fma_f32 v[8:9], v[8:9], v[2:3], v[12:13]
	v_pk_fma_f32 v[2:3], v[10:11], v[2:3], v[14:15]
	s_cbranch_vccz .LBB0_1270
	v_cvt_pk_bf16_f32 v10, v8, v9
	v_cvt_pk_bf16_f32 v11, v2, v3
	global_store_dwordx2 v[152:153], v[10:11], off offset:480
	s_mov_b64 s[4:5], 0
	s_branch .LBB0_1270
